# last three butterfly steps of the rmsnorm gate reduction done with DPP row ops (both norm instances), on top of the best version
# baseline (speedup 1.0000x reference)
; __device__ __forceinline__ unsigned pk2(float lo, float hi) { f32x2_t v = {lo, hi}; bf16x2_hw b = __builtin_convertvector(v, bf16x2_hw); return __builtin_bit_cast(unsigned, b); }
; template <bool BIN, bool WRITE_U> __device__ __forceinline__ void norm_phase(const void* hin_, const float* gain, bf16* U, const float* Wg, int ldw, int goff, int ng, float* GATE, float* RSTD, unsigned char* lds) {
;     ...
;         if (WRITE_U) { unsigned long long* o8 = (unsigned long long*)(U + (size_t)row * D_) + lane;
; #pragma unroll
;             for (int j = 0; j < 4; ++j) o8[64 * j] = (unsigned long long)pk2(v[j].x, v[j].y) | ((unsigned long long)pk2(v[j].z, v[j].w) << 32); }
;         if (ng > 0) {
;             float acc[8];
; #pragma unroll
;             for (int g = 0; g < 8; ++g) acc[g] = 0.f;
; #pragma unroll
;             for (int j = 0; j < 4; ++j)
; #pragma unroll
;                 for (int e = 0; e < 4; ++e) { const int k = 4 * (lane + 64 * j) + e; const f32x4 w0 = *(const f32x4*)(wl + k * 8), w1 = *(const f32x4*)(wl + k * 8 + 4); const float x = v[j][e];
;                     acc[0] += x * w0.x; acc[1] += x * w0.y; acc[2] += x * w0.z; acc[3] += x * w0.w; acc[4] += x * w1.x; acc[5] += x * w1.y; acc[6] += x * w1.z; acc[7] += x * w1.w; }
;             const bool h5 = (lane & 32) != 0, h4 = (lane & 16) != 0, h3 = (lane & 8) != 0;
;             float b4[4], c2[2];
; #pragma unroll
;             for (int i = 0; i < 4; ++i) { const float snd = h5 ? acc[i] : acc[i + 4], kp = h5 ? acc[i + 4] : acc[i]; b4[i] = kp + __shfl_xor(snd, 32); }
; #pragma unroll
;             for (int i = 0; i < 2; ++i) { const float snd = h4 ? b4[i] : b4[i + 2], kp = h4 ? b4[i + 2] : b4[i]; c2[i] = kp + __shfl_xor(snd, 16); }
;             float dsum; { const float snd = h3 ? c2[0] : c2[1], kp = h3 ? c2[1] : c2[0]; dsum = kp + __shfl_xor(snd, 8); }
;             dsum += __shfl_xor(dsum, 4); dsum += __shfl_xor(dsum, 2); dsum += __shfl_xor(dsum, 1);
;             if ((lane & 7) == 0) GATE[(size_t)row * 8 + ((lane >> 3) & 1) + 2 * ((lane >> 4) & 1) + 4 * ((lane >> 5) & 1)] = dsum * rstd;
.LBB0_218:
	s_or_b64 exec, exec, s[12:13]
	v_ashrrev_i32_e32 v187, 31, v186
	v_lshlrev_b64 v[180:181], 11, v[186:187]
	v_lshl_add_u64 v[180:181], v[190:191], 0, v[180:181]
	v_cvt_pk_bf16_f32 v182, v174, v175
	v_cvt_pk_bf16_f32 v183, v176, v177
	global_store_dwordx2 v[180:181], v[182:183], off
	v_cvt_pk_bf16_f32 v182, v170, v171
	v_cvt_pk_bf16_f32 v183, v172, v173
	global_store_dwordx2 v[180:181], v[182:183], off offset:512
	v_cvt_pk_bf16_f32 v182, v166, v167
	v_cvt_pk_bf16_f32 v183, v168, v169
	global_store_dwordx2 v[180:181], v[182:183], off offset:1024
	v_cvt_pk_bf16_f32 v182, v162, v163
	v_cvt_pk_bf16_f32 v183, v164, v165
	global_store_dwordx2 v[180:181], v[182:183], off offset:1536
	v_fma_f32 v180, v174, v18, 0
	v_fma_f32 v200, v174, v22, 0
	v_fmac_f32_e32 v180, v175, v26
	v_fmac_f32_e32 v200, v175, v30
	v_fmac_f32_e32 v180, v176, v34
	v_fmac_f32_e32 v200, v176, v38
	v_fmac_f32_e32 v180, v177, v42
	v_fmac_f32_e32 v200, v177, v46
	v_fma_f32 v181, v174, v19, 0
	v_fma_f32 v182, v174, v20, 0
	v_fma_f32 v183, v174, v21, 0
	v_fma_f32 v201, v174, v23, 0
	v_fma_f32 v202, v174, v24, 0
	v_fma_f32 v174, v174, v25, 0
	v_fmac_f32_e32 v180, v170, v50
	v_fmac_f32_e32 v200, v170, v54
	v_fmac_f32_e32 v181, v175, v27
	v_fmac_f32_e32 v182, v175, v28
	v_fmac_f32_e32 v183, v175, v29
	v_fmac_f32_e32 v201, v175, v31
	v_fmac_f32_e32 v202, v175, v32
	v_fmac_f32_e32 v174, v175, v33
	v_fmac_f32_e32 v180, v171, v58
	v_fmac_f32_e32 v200, v171, v62
	v_fmac_f32_e32 v181, v176, v35
	v_fmac_f32_e32 v182, v176, v36
	v_fmac_f32_e32 v183, v176, v37
	v_fmac_f32_e32 v201, v176, v39
	v_fmac_f32_e32 v202, v176, v40
	v_fmac_f32_e32 v174, v176, v41
	v_fmac_f32_e32 v180, v172, v66
	v_fmac_f32_e32 v200, v172, v70
	v_fmac_f32_e32 v181, v177, v43
	v_fmac_f32_e32 v182, v177, v44
	v_fmac_f32_e32 v183, v177, v45
	v_fmac_f32_e32 v201, v177, v47
	v_fmac_f32_e32 v202, v177, v48
	v_fmac_f32_e32 v174, v177, v49
	v_fmac_f32_e32 v180, v173, v74
	v_fmac_f32_e32 v200, v173, v78
	v_fmac_f32_e32 v181, v170, v51
	v_fmac_f32_e32 v182, v170, v52
	v_fmac_f32_e32 v183, v170, v53
	v_fmac_f32_e32 v201, v170, v55
	v_fmac_f32_e32 v202, v170, v56
	v_fmac_f32_e32 v174, v170, v57
	v_fmac_f32_e32 v180, v166, v82
	v_fmac_f32_e32 v200, v166, v86
	v_fmac_f32_e32 v181, v171, v59
	v_fmac_f32_e32 v182, v171, v60
	v_fmac_f32_e32 v183, v171, v61
	v_fmac_f32_e32 v201, v171, v63
	v_fmac_f32_e32 v202, v171, v64
	v_fmac_f32_e32 v174, v171, v65
	v_fmac_f32_e32 v180, v167, v90
	v_fmac_f32_e32 v200, v167, v94
	v_fmac_f32_e32 v181, v172, v67
	v_fmac_f32_e32 v182, v172, v68
	v_fmac_f32_e32 v183, v172, v69
	v_fmac_f32_e32 v201, v172, v71
	v_fmac_f32_e32 v202, v172, v72
	v_fmac_f32_e32 v174, v172, v73
	v_fmac_f32_e32 v180, v168, v98
	v_fmac_f32_e32 v200, v168, v102
	v_fmac_f32_e32 v181, v173, v75
	v_fmac_f32_e32 v182, v173, v76
	v_fmac_f32_e32 v183, v173, v77
	v_fmac_f32_e32 v201, v173, v79
	v_fmac_f32_e32 v202, v173, v80
	v_fmac_f32_e32 v174, v173, v81
	v_fmac_f32_e32 v180, v169, v106
	v_fmac_f32_e32 v200, v169, v110
	v_fmac_f32_e32 v181, v166, v83
	v_fmac_f32_e32 v182, v166, v84
	v_fmac_f32_e32 v183, v166, v85
	v_fmac_f32_e32 v201, v166, v87
	v_fmac_f32_e32 v202, v166, v88
	v_fmac_f32_e32 v174, v166, v89
	v_fmac_f32_e32 v180, v162, v114
	v_fmac_f32_e32 v200, v162, v118
	v_fmac_f32_e32 v181, v167, v91
	v_fmac_f32_e32 v182, v167, v92
	v_fmac_f32_e32 v183, v167, v93
	v_fmac_f32_e32 v201, v167, v95
	v_fmac_f32_e32 v202, v167, v96
	v_fmac_f32_e32 v174, v167, v97
	v_fmac_f32_e32 v180, v163, v122
	v_fmac_f32_e32 v200, v163, v126
	v_fmac_f32_e32 v181, v168, v99
	v_fmac_f32_e32 v182, v168, v100
	v_fmac_f32_e32 v183, v168, v101
	v_fmac_f32_e32 v201, v168, v103
	v_fmac_f32_e32 v202, v168, v104
	v_fmac_f32_e32 v174, v168, v105
	v_fmac_f32_e32 v180, v164, v130
	v_fmac_f32_e32 v200, v164, v134
	v_fmac_f32_e32 v181, v169, v107
	v_fmac_f32_e32 v182, v169, v108
	v_fmac_f32_e32 v183, v169, v109
	v_fmac_f32_e32 v201, v169, v111
	v_fmac_f32_e32 v202, v169, v112
	v_fmac_f32_e32 v174, v169, v113
	v_fmac_f32_e32 v180, v165, v138
	v_fmac_f32_e32 v200, v165, v142
	v_fmac_f32_e32 v181, v162, v115
	v_fmac_f32_e32 v182, v162, v116
	v_fmac_f32_e32 v183, v162, v117
	v_fmac_f32_e32 v201, v162, v119
	v_fmac_f32_e32 v202, v162, v120
	v_fmac_f32_e32 v174, v162, v121
	v_cndmask_b32_e64 v162, v180, v200, s[4:5]
	ds_bpermute_b32 v162, v199, v162
	v_fmac_f32_e32 v181, v163, v123
	v_fmac_f32_e32 v201, v163, v127
	v_fmac_f32_e32 v181, v164, v131
	v_fmac_f32_e32 v201, v164, v135
	v_fmac_f32_e32 v182, v163, v124
	v_fmac_f32_e32 v183, v163, v125
	v_fmac_f32_e32 v202, v163, v128
	v_fmac_f32_e32 v174, v163, v129
	v_fmac_f32_e32 v181, v165, v139
	v_fmac_f32_e32 v201, v165, v143
	v_cndmask_b32_e64 v163, v200, v180, s[4:5]
	s_waitcnt lgkmcnt(0)
	v_add_f32_e32 v162, v163, v162
	v_cndmask_b32_e64 v163, v181, v201, s[4:5]
	ds_bpermute_b32 v163, v199, v163
	v_fmac_f32_e32 v182, v164, v132
	v_fmac_f32_e32 v202, v164, v136
	v_fmac_f32_e32 v183, v164, v133
	v_fmac_f32_e32 v174, v164, v137
	v_fmac_f32_e32 v182, v165, v140
	v_fmac_f32_e32 v202, v165, v144
	v_cndmask_b32_e64 v164, v201, v181, s[4:5]
	s_waitcnt lgkmcnt(0)
	v_add_f32_e32 v163, v164, v163
	v_cndmask_b32_e64 v164, v182, v202, s[4:5]
	ds_bpermute_b32 v164, v199, v164
	v_fmac_f32_e32 v183, v165, v141
	v_fmac_f32_e32 v174, v165, v145
	v_cndmask_b32_e64 v165, v202, v182, s[4:5]
	v_cndmask_b32_e64 v166, v174, v183, s[4:5]
	s_waitcnt lgkmcnt(0)
	v_add_f32_e32 v164, v165, v164
	v_cndmask_b32_e64 v165, v183, v174, s[4:5]
	ds_bpermute_b32 v165, v199, v165
	s_waitcnt lgkmcnt(0)
	v_add_f32_e32 v165, v166, v165
	v_cndmask_b32_e64 v166, v162, v164, s[6:7]
	v_cndmask_b32_e64 v162, v164, v162, s[6:7]
	ds_bpermute_b32 v164, v198, v166
	s_waitcnt lgkmcnt(0)
	v_add_f32_e32 v162, v162, v164
	v_cndmask_b32_e64 v164, v163, v165, s[6:7]
	ds_bpermute_b32 v164, v198, v164
	v_cndmask_b32_e64 v163, v165, v163, s[6:7]
	s_waitcnt lgkmcnt(0)
	v_add_f32_e32 v163, v163, v164
	v_cndmask_b32_e64 v164, v162, v163, s[8:9]
	v_cndmask_b32_e64 v162, v163, v162, s[8:9]
	ds_bpermute_b32 v163, v197, v164
	s_waitcnt lgkmcnt(0)
	v_add_f32_e32 v162, v162, v163
	s_nop 1
	v_add_f32_dpp v162, v162, v162 row_shl:4 row_mask:0xf bank_mask:0xf
	s_nop 1
	v_add_f32_dpp v162, v162, v162 quad_perm:[2,3,0,1] row_mask:0xf bank_mask:0xf
	s_nop 1
	v_add_f32_dpp v162, v162, v162 quad_perm:[1,0,3,2] row_mask:0xf bank_mask:0xf
	s_and_saveexec_b64 s[12:13], s[10:11]
	s_cbranch_execz .LBB0_213
	v_lshlrev_b64 v[164:165], 5, v[186:187]
	s_waitcnt lgkmcnt(0)
	v_lshl_add_u64 v[164:165], v[192:193], 0, v[164:165]
	v_mul_f32_e32 v162, v195, v162
	global_store_dword v[164:165], v162, off
	s_branch .LBB0_213
